# S5 scan items and first-norm rows XCD-aligned; norm1->pass1 and pass2->GLU seams XCC-local (22 of 29 local, 7 grid barriers left)
# speedup vs baseline: 1.0672x; 1.0057x over previous
.LBB0_190:
	s_andn2_b64 vcc, exec, s[4:5]
	s_cbranch_vccnz .LBB0_226
	v_readlane_b32 s4, v240, 10
	v_writelane_b32 v239, s84, 57
	v_readlane_b32 s5, v240, 11
	s_andn2_b64 vcc, exec, s[4:5]
	v_writelane_b32 v239, s85, 58
	v_readfirstlane_b32 s3, v210
	v_writelane_b32 v239, s80, 59
	s_cbranch_vccnz .LBB0_225
	s_ashr_i32 s5, s3, 6
	s_mul_i32 s3, s5, 0x2200
	v_and_b32_e32 v166, 63, v211
	s_add_i32 s3, s3, 0
	v_and_b32_e32 v168, 31, v211
	v_bfe_u32 v167, v211, 5, 1
	v_lshlrev_b32_e32 v1, 1, v166
	s_add_i32 s3, s3, 0x11000
	s_movk_i32 s4, 0x1000
	v_or_b32_e32 v0, 64, v1
	v_or_b32_e32 v2, 0x41, v1
	v_lshrrev_b32_e32 v1, 1, v211
	v_lshlrev_b32_e32 v3, 5, v211
	v_lshlrev_b32_e32 v5, 2, v168
	v_mul_u32_u24_e32 v6, 0x1100, v167
	v_cmp_gt_i32_e64 s[12:13], s4, v210
	v_readlane_b32 s10, v239, 47
	v_and_b32_e32 v3, 0x80, v3
	v_and_b32_e32 v1, 12, v1
	v_and_b32_e32 v4, 3, v211
	s_lshl_b32 s4, s5, 5
	v_add3_u32 v169, s3, v5, v6
	v_and_b32_e32 v5, 15, v211
	v_lshrrev_b32_e32 v7, 2, v211
	s_lshl_b32 s7, s10, 7
	v_or3_b32 v1, v3, v1, v4
	v_writelane_b32 v238, s5, 0
	s_add_i32 s6, s4, 0
	v_lshlrev_b32_e32 v4, 4, v167
	v_and_b32_e32 v6, 48, v211
	v_mul_u32_u24_e32 v10, 0x110, v5
	v_and_b32_e32 v11, 12, v7
	v_lshlrev_b32_e32 v164, 4, v5
	v_add_u32_e32 v3, s6, v4
	v_add3_u32 v171, s3, v6, v10
	v_writelane_b32 v238, s7, 2
	s_or_b32 s3, s7, 64
	v_lshl_add_u32 v12, v11, 1, s6
	v_lshl_add_u64 v[8:9], s[42:43], 0, v[164:165]
	s_mov_b64 s[6:7], 0x8900000
	v_mov_b32_e32 v5, v165
	v_lshl_add_u64 v[172:173], v[8:9], 0, s[6:7]
	v_add_u32_e32 v174, 0, v164
	s_mov_b64 s[6:7], 0x9900000
	v_lshl_add_u64 v[4:5], s[42:43], 0, v[4:5]
	v_lshlrev_b32_e32 v164, 5, v168
	v_lshl_add_u64 v[176:177], v[8:9], 0, s[6:7]
	v_lshl_add_u64 v[4:5], v[4:5], 0, v[164:165]
	s_mov_b64 s[6:7], 0x100000
	v_cmp_gt_u32_e64 s[8:9], 32, v166
	s_lshl_b32 s4, s10, 10
	v_lshl_add_u64 v[178:179], v[4:5], 0, s[6:7]
	v_lshlrev_b32_e32 v4, 8, v211
	v_readlane_b32 s11, v239, 48
	v_writelane_b32 v239, s8, 60
	v_writelane_b32 v238, s3, 3
	s_or_b32 s3, s79, 1
	s_ashr_i32 s5, s4, 31
	v_and_b32_e32 v164, 0xf00, v4
	v_writelane_b32 v239, s9, 61
	v_cmp_lt_u32_e64 s[8:9], 31, v166
	s_add_u32 s65, s42, 0x300000
	v_lshl_add_u64 v[4:5], s[42:43], 0, v[164:165]
	v_mov_b32_e32 v7, v165
	v_writelane_b32 v239, s8, 62
	s_addc_u32 s72, s43, 0
	v_lshl_add_u64 v[4:5], v[4:5], 0, v[6:7]
	s_mov_b64 s[6:7], 0x200000
	v_writelane_b32 v239, s9, 63
	v_lshl_add_u64 v[180:181], v[4:5], 0, s[6:7]
	s_add_u32 s6, s42, 0x380000
	s_addc_u32 s7, s43, 0
	s_mov_b64 s[8:9], s[58:59]
	v_readlane_b32 s52, v239, 21
	v_writelane_b32 v238, s3, 4
	s_add_u32 s3, s42, 0x400000
	v_readlane_b32 s58, v239, 27
	v_readlane_b32 s59, v239, 28
	v_writelane_b32 v238, s3, 5
	s_addc_u32 s3, s43, 0
	s_mov_b64 s[14:15], s[58:59]
	s_add_u32 s10, s14, 0x2000000
	s_addc_u32 s11, s15, 0
	s_add_u32 s18, s14, 0x2100000
	s_addc_u32 s19, s15, 0
	v_writelane_b32 v238, s3, 6
	s_add_u32 s3, s42, 0x600000
	v_writelane_b32 v238, s3, 7
	s_addc_u32 s3, s43, 0
	s_lshl_b64 s[4:5], s[4:5], 2
	s_add_u32 s4, s38, s4
	v_mul_u32_u24_e32 v1, 0x110, v1
	v_writelane_b32 v238, s3, 8
	s_addc_u32 s5, s39, s5
	v_lshlrev_b32_e32 v164, 2, v11
	v_lshlrev_b32_e32 v170, 1, v168
	s_mov_b64 s[58:59], s[8:9]
	v_lshl_add_u64 v[182:183], s[4:5], 0, v[164:165]
	v_lshlrev_b32_e32 v184, 2, v0
	v_lshlrev_b32_e32 v186, 2, v2
	v_add_u32_e32 v175, v12, v10
	v_add_u32_e32 v212, v3, v1
	v_readlane_b32 s8, v240, 0
	s_and_b32 s98, s8, 7
	s_lshl_b32 s98, s98, 5
	s_and_b32 s99, s8, 0x18
	s_add_i32 s98, s98, s99
	s_lshr_b32 s99, s8, 5
	s_add_i32 s8, s98, s99
	v_writelane_b32 v238, s78, 9
	v_readlane_b32 s53, v239, 22
	v_readlane_b32 s54, v239, 23
	v_readlane_b32 s55, v239, 24
	v_readlane_b32 s56, v239, 25
	v_readlane_b32 s57, v239, 26
	v_writelane_b32 v238, s79, 11
	s_branch .LBB0_194

.LBB0_252:
	s_andn2_b64 vcc, exec, s[4:5]
	s_cbranch_vccnz .LBB0_262
	v_readlane_b32 s4, v240, 10
	v_readlane_b32 s5, v240, 11
	s_mov_b64 s[46:47], s[84:85]
	s_mov_b32 s38, s80
	s_andn2_b64 vcc, exec, s[4:5]
	v_readfirstlane_b32 s3, v210
	s_cbranch_vccnz .LBB0_261
	v_readlane_b32 s6, v239, 47
	v_lshlrev_b32_e32 v2, 5, v211
	v_lshlrev_b32_e32 v3, 4, v211
	v_bfe_u32 v119, v211, 5, 1
	v_readlane_b32 s7, v239, 48
	v_and_b32_e32 v6, 0x80, v2
	v_lshrrev_b32_e32 v2, 1, v211
	v_and_b32_e32 v164, 0xf0, v3
	v_and_b32_e32 v1, 31, v211
	s_lshl_b32 s12, s6, 7
	v_and_b32_e32 v7, 12, v2
	v_lshlrev_b32_e32 v2, 4, v119
	v_lshl_add_u64 v[4:5], s[42:43], 0, v[164:165]
	s_mov_b64 s[6:7], 0x8900000
	v_mov_b32_e32 v3, v165
	v_lshl_add_u64 v[116:117], v[4:5], 0, s[6:7]
	v_add_u32_e32 v118, 0, v164
	v_lshl_add_u64 v[4:5], s[42:43], 0, v[2:3]
	v_lshlrev_b32_e32 v164, 5, v1
	s_ashr_i32 s3, s3, 6
	v_lshl_add_u64 v[4:5], v[4:5], 0, v[164:165]
	s_mov_b64 s[8:9], 0x100000
	v_lshlrev_b32_e32 v164, 3, v1
	v_and_b32_e32 v8, 3, v211
	s_lshl_b32 s10, s3, 5
	v_lshl_add_u64 v[120:121], v[4:5], 0, s[8:9]
	v_lshl_add_u64 v[4:5], s[42:43], 0, v[164:165]
	s_mov_b64 s[8:9], 0x300000
	v_lshlrev_b32_e32 v0, 1, v1
	v_lshl_add_u64 v[122:123], v[4:5], 0, s[8:9]
	v_or3_b32 v1, v6, v7, v8
	v_mov_b32_e32 v3, s10
	s_movk_i32 s8, 0x110
	s_movk_i32 s4, 0x1000
	s_add_u32 s6, s42, 0x400000
	v_mad_u32_u24 v1, v1, s8, v3
	v_cmp_gt_i32_e64 s[4:5], s4, v210
	s_addc_u32 s7, s43, 0
	v_add3_u32 v172, v1, v2, 0
	v_lshlrev_b32_e32 v164, 2, v0
	v_readlane_b32 s13, v240, 0
	s_and_b32 s98, s13, 7
	s_lshl_b32 s98, s98, 5
	s_and_b32 s99, s13, 0x18
	s_add_i32 s98, s98, s99
	s_lshr_b32 s99, s13, 5
	s_add_i32 s13, s98, s99

.LBB0_293:
	v_readlane_b32 s72, v239, 17
	s_andn2_b64 vcc, exec, s[66:67]
	v_readlane_b32 s73, v239, 18
	s_cbranch_vccnz .LBB0_348
	s_waitcnt lgkmcnt(0)
	v_readlane_b32 s46, v239, 29
	v_readlane_b32 s47, v239, 30
	s_lshl_b32 s7, s79, 12
	s_add_u32 s16, s16, s7
	s_addc_u32 s17, s17, 0
	v_readlane_b32 s14, v239, 51
	v_readlane_b32 s15, v239, 52
	s_add_i32 s3, s70, 5
	s_cmp_lt_u32 s3, 13
	s_cbranch_scc0 .Lnorm1_regular
	v_readlane_b32 s18, v239, 31
	v_readlane_b32 s19, v239, 32
	v_readlane_b32 s34, v239, 33
	v_readlane_b32 s35, v239, 34
	v_and_b32_e32 v8, 63, v211
	v_lshlrev_b32_e32 v0, 5, v8
	v_lshlrev_b32_e32 v1, 4, v8
	v_lshlrev_b32_e32 v9, 2, v8
	v_xor_b32_e32 v2, 0x4, v9
	v_xor_b32_e32 v3, 0x8, v9
	v_xor_b32_e32 v4, 0x10, v9
	v_xor_b32_e32 v5, 0x20, v9
	v_xor_b32_e32 v6, 0x40, v9
	v_xor_b32_e32 v7, 0x80, v9
	v_readlane_b32 s3, v240, 55
	v_readlane_b32 s6, v239, 10
	s_lshr_b32 s3, s3, 6
	s_lshl_b32 s3, s3, 2
	s_and_b32 s7, s78, 7
	s_lshl_b32 s7, s7, 10
	s_add_i32 s3, s3, s7
	s_lshr_b32 s7, s78, 3
	s_lshl_b32 s7, s7, 5
	s_add_i32 s3, s3, s7
	s_lshl_b32 s6, s6, 3
	s_cmpk_lt_i32 s3, 0x2000
	s_cbranch_scc0 .Lnorm1f_end
.Lnorm1f_loop:
	s_mov_b32 s8, s3
	s_add_i32 s9, s8, 1
	s_add_i32 s10, s9, 1
	s_add_i32 s11, s10, 1
	s_cmpk_lt_i32 s9, 0x2000
	s_cselect_b32 s9, s9, s3
	s_cmpk_lt_i32 s10, 0x2000
	s_cselect_b32 s10, s10, s3
	s_cmpk_lt_i32 s11, 0x2000
	s_cselect_b32 s11, s11, s3
	s_cmpk_lt_i32 s8, 0x1000
	s_cselect_b32 s4, s18, s34
	s_cselect_b32 s5, s19, s35
	s_and_b32 s7, s8, 0xfff
	s_lshl_b32 s7, s7, 12
	s_add_u32 s4, s4, s7
	s_addc_u32 s5, s5, 0
	global_load_dwordx4 v[16:19], v0, s[4:5] nt
	global_load_dwordx4 v[20:23], v0, s[4:5] offset:16 nt
	global_load_dwordx4 v[24:27], v0, s[4:5] offset:2048 nt
	global_load_dwordx4 v[28:31], v0, s[4:5] offset:2064 nt
	s_cmpk_lt_i32 s9, 0x1000
	s_cselect_b32 s4, s18, s34
	s_cselect_b32 s5, s19, s35
	s_and_b32 s7, s9, 0xfff
	s_lshl_b32 s7, s7, 12
	s_add_u32 s4, s4, s7
	s_addc_u32 s5, s5, 0
	global_load_dwordx4 v[32:35], v0, s[4:5] nt
	global_load_dwordx4 v[36:39], v0, s[4:5] offset:16 nt
	global_load_dwordx4 v[40:43], v0, s[4:5] offset:2048 nt
	global_load_dwordx4 v[44:47], v0, s[4:5] offset:2064 nt
	s_cmpk_lt_i32 s10, 0x1000
	s_cselect_b32 s4, s18, s34
	s_cselect_b32 s5, s19, s35
	s_and_b32 s7, s10, 0xfff
	s_lshl_b32 s7, s7, 12
	s_add_u32 s4, s4, s7
	s_addc_u32 s5, s5, 0
	global_load_dwordx4 v[48:51], v0, s[4:5] nt
	global_load_dwordx4 v[52:55], v0, s[4:5] offset:16 nt
	global_load_dwordx4 v[56:59], v0, s[4:5] offset:2048 nt
	global_load_dwordx4 v[60:63], v0, s[4:5] offset:2064 nt
	s_cmpk_lt_i32 s11, 0x1000
	s_cselect_b32 s4, s18, s34
	s_cselect_b32 s5, s19, s35
	s_and_b32 s7, s11, 0xfff
	s_lshl_b32 s7, s7, 12
	s_add_u32 s4, s4, s7
	s_addc_u32 s5, s5, 0
	global_load_dwordx4 v[64:67], v0, s[4:5] nt
	global_load_dwordx4 v[68:71], v0, s[4:5] offset:16 nt
	global_load_dwordx4 v[72:75], v0, s[4:5] offset:2048 nt
	global_load_dwordx4 v[76:79], v0, s[4:5] offset:2064 nt
	global_load_dwordx4 v[80:83], v0, s[16:17]
	global_load_dwordx4 v[84:87], v0, s[16:17] offset:16
	global_load_dwordx4 v[88:91], v0, s[16:17] offset:2048
	global_load_dwordx4 v[92:95], v0, s[16:17] offset:2064
	s_sub_i32 s7, s8, 0x1000
	s_lshr_b32 s7, s7, 11
	s_add_i32 s7, s7, 1
	s_cmpk_lt_i32 s8, 0x1000
	s_cselect_b32 s7, 0, s7
	s_mulk_i32 s7, 0x6000
	s_add_i32 s7, s7, 0x0
	s_add_u32 s4, s14, s7
	s_addc_u32 s5, s15, 0
	global_load_dwordx4 v[112:115], v0, s[4:5]
	global_load_dwordx4 v[116:119], v0, s[4:5] offset:16
	global_load_dwordx4 v[120:123], v0, s[4:5] offset:2048
	global_load_dwordx4 v[124:127], v0, s[4:5] offset:2064
	s_add_u32 s4, s4, 0x1000
	s_addc_u32 s5, s5, 0
	global_load_dwordx4 v[96:99], v0, s[4:5]
	global_load_dwordx4 v[100:103], v0, s[4:5] offset:16
	global_load_dwordx4 v[104:107], v0, s[4:5] offset:2048
	global_load_dwordx4 v[108:111], v0, s[4:5] offset:2064
	s_sub_i32 s7, s9, 0x1000
	s_lshr_b32 s7, s7, 11
	s_add_i32 s7, s7, 1
	s_cmpk_lt_i32 s9, 0x1000
	s_cselect_b32 s7, 0, s7
	s_mulk_i32 s7, 0x6000
	s_add_i32 s7, s7, 0x0
	s_add_u32 s4, s14, s7
	s_addc_u32 s5, s15, 0
	global_load_dwordx4 v[144:147], v0, s[4:5]
	global_load_dwordx4 v[148:151], v0, s[4:5] offset:16
	global_load_dwordx4 v[152:155], v0, s[4:5] offset:2048
	global_load_dwordx4 v[156:159], v0, s[4:5] offset:2064
	s_add_u32 s4, s4, 0x1000
	s_addc_u32 s5, s5, 0
	global_load_dwordx4 v[128:131], v0, s[4:5]
	global_load_dwordx4 v[132:135], v0, s[4:5] offset:16
	global_load_dwordx4 v[136:139], v0, s[4:5] offset:2048
	global_load_dwordx4 v[140:143], v0, s[4:5] offset:2064
	s_waitcnt vmcnt(32)
	s_lshl_b32 s7, s8, 12
	s_add_u32 s4, s46, s7
	s_addc_u32 s5, s47, 0
	s_add_u32 s4, s4, 0x6900000
	s_addc_u32 s5, s5, 0
	global_store_dwordx4 v0, v[16:19], s[4:5]
	global_store_dwordx4 v0, v[20:23], s[4:5] offset:16
	global_store_dwordx4 v0, v[24:27], s[4:5] offset:2048
	global_store_dwordx4 v0, v[28:31], s[4:5] offset:2064
	v_mul_f32_e32 v160, v17, v17
	v_mul_f32_e32 v9, v19, v19
	v_fmac_f32_e32 v160, v16, v16
	v_fmac_f32_e32 v9, v18, v18
	v_add_f32_e32 v160, v160, v9
	v_mul_f32_e32 v8, v21, v21
	v_mul_f32_e32 v9, v23, v23
	v_fmac_f32_e32 v8, v20, v20
	v_fmac_f32_e32 v9, v22, v22
	v_add_f32_e32 v8, v8, v9
	v_add_f32_e32 v160, v160, v8
	v_mul_f32_e32 v8, v25, v25
	v_mul_f32_e32 v9, v27, v27
	v_fmac_f32_e32 v8, v24, v24
	v_fmac_f32_e32 v9, v26, v26
	v_add_f32_e32 v8, v8, v9
	v_add_f32_e32 v160, v160, v8
	v_mul_f32_e32 v8, v29, v29
	v_mul_f32_e32 v9, v31, v31
	v_fmac_f32_e32 v8, v28, v28
	v_fmac_f32_e32 v9, v30, v30
	v_add_f32_e32 v8, v8, v9
	v_add_f32_e32 v160, v160, v8
	s_waitcnt vmcnt(32)
	s_lshl_b32 s7, s9, 12
	s_add_u32 s4, s46, s7
	s_addc_u32 s5, s47, 0
	s_add_u32 s4, s4, 0x6900000
	s_addc_u32 s5, s5, 0
	global_store_dwordx4 v0, v[32:35], s[4:5]
	global_store_dwordx4 v0, v[36:39], s[4:5] offset:16
	global_store_dwordx4 v0, v[40:43], s[4:5] offset:2048
	global_store_dwordx4 v0, v[44:47], s[4:5] offset:2064
	v_mul_f32_e32 v161, v33, v33
	v_mul_f32_e32 v9, v35, v35
	v_fmac_f32_e32 v161, v32, v32
	v_fmac_f32_e32 v9, v34, v34
	v_add_f32_e32 v161, v161, v9
	v_mul_f32_e32 v8, v37, v37
	v_mul_f32_e32 v9, v39, v39
	v_fmac_f32_e32 v8, v36, v36
	v_fmac_f32_e32 v9, v38, v38
	v_add_f32_e32 v8, v8, v9
	v_add_f32_e32 v161, v161, v8
	v_mul_f32_e32 v8, v41, v41
	v_mul_f32_e32 v9, v43, v43
	v_fmac_f32_e32 v8, v40, v40
	v_fmac_f32_e32 v9, v42, v42
	v_add_f32_e32 v8, v8, v9
	v_add_f32_e32 v161, v161, v8
	v_mul_f32_e32 v8, v45, v45
	v_mul_f32_e32 v9, v47, v47
	v_fmac_f32_e32 v8, v44, v44
	v_fmac_f32_e32 v9, v46, v46
	v_add_f32_e32 v8, v8, v9
	v_add_f32_e32 v161, v161, v8
	s_waitcnt vmcnt(32)
	s_lshl_b32 s7, s10, 12
	s_add_u32 s4, s46, s7
	s_addc_u32 s5, s47, 0
	s_add_u32 s4, s4, 0x6900000
	s_addc_u32 s5, s5, 0
	global_store_dwordx4 v0, v[48:51], s[4:5]
	global_store_dwordx4 v0, v[52:55], s[4:5] offset:16
	global_store_dwordx4 v0, v[56:59], s[4:5] offset:2048
	global_store_dwordx4 v0, v[60:63], s[4:5] offset:2064
	v_mul_f32_e32 v162, v49, v49
	v_mul_f32_e32 v9, v51, v51
	v_fmac_f32_e32 v162, v48, v48
	v_fmac_f32_e32 v9, v50, v50
	v_add_f32_e32 v162, v162, v9
	v_mul_f32_e32 v8, v53, v53
	v_mul_f32_e32 v9, v55, v55
	v_fmac_f32_e32 v8, v52, v52
	v_fmac_f32_e32 v9, v54, v54
	v_add_f32_e32 v8, v8, v9
	v_add_f32_e32 v162, v162, v8
	v_mul_f32_e32 v8, v57, v57
	v_mul_f32_e32 v9, v59, v59
	v_fmac_f32_e32 v8, v56, v56
	v_fmac_f32_e32 v9, v58, v58
	v_add_f32_e32 v8, v8, v9
	v_add_f32_e32 v162, v162, v8
	v_mul_f32_e32 v8, v61, v61
	v_mul_f32_e32 v9, v63, v63
	v_fmac_f32_e32 v8, v60, v60
	v_fmac_f32_e32 v9, v62, v62
	v_add_f32_e32 v8, v8, v9
	v_add_f32_e32 v162, v162, v8
	s_waitcnt vmcnt(32)
	s_lshl_b32 s7, s11, 12
	s_add_u32 s4, s46, s7
	s_addc_u32 s5, s47, 0
	s_add_u32 s4, s4, 0x6900000
	s_addc_u32 s5, s5, 0
	global_store_dwordx4 v0, v[64:67], s[4:5]
	global_store_dwordx4 v0, v[68:71], s[4:5] offset:16
	global_store_dwordx4 v0, v[72:75], s[4:5] offset:2048
	global_store_dwordx4 v0, v[76:79], s[4:5] offset:2064
	v_mul_f32_e32 v163, v65, v65
	v_mul_f32_e32 v9, v67, v67
	v_fmac_f32_e32 v163, v64, v64
	v_fmac_f32_e32 v9, v66, v66
	v_add_f32_e32 v163, v163, v9
	v_mul_f32_e32 v8, v69, v69
	v_mul_f32_e32 v9, v71, v71
	v_fmac_f32_e32 v8, v68, v68
	v_fmac_f32_e32 v9, v70, v70
	v_add_f32_e32 v8, v8, v9
	v_add_f32_e32 v163, v163, v8
	v_mul_f32_e32 v8, v73, v73
	v_mul_f32_e32 v9, v75, v75
	v_fmac_f32_e32 v8, v72, v72
	v_fmac_f32_e32 v9, v74, v74
	v_add_f32_e32 v8, v8, v9
	v_add_f32_e32 v163, v163, v8
	v_mul_f32_e32 v8, v77, v77
	v_mul_f32_e32 v9, v79, v79
	v_fmac_f32_e32 v8, v76, v76
	v_fmac_f32_e32 v9, v78, v78
	v_add_f32_e32 v8, v8, v9
	v_add_f32_e32 v163, v163, v8
	ds_bpermute_b32 v8, v2, v160
	ds_bpermute_b32 v9, v2, v161
	ds_bpermute_b32 v10, v2, v162
	ds_bpermute_b32 v11, v2, v163
	s_waitcnt lgkmcnt(3)
	v_add_f32_e32 v160, v160, v8
	s_waitcnt lgkmcnt(2)
	v_add_f32_e32 v161, v161, v9
	s_waitcnt lgkmcnt(1)
	v_add_f32_e32 v162, v162, v10
	s_waitcnt lgkmcnt(0)
	v_add_f32_e32 v163, v163, v11
	ds_bpermute_b32 v8, v3, v160
	ds_bpermute_b32 v9, v3, v161
	ds_bpermute_b32 v10, v3, v162
	ds_bpermute_b32 v11, v3, v163
	s_waitcnt lgkmcnt(3)
	v_add_f32_e32 v160, v160, v8
	s_waitcnt lgkmcnt(2)
	v_add_f32_e32 v161, v161, v9
	s_waitcnt lgkmcnt(1)
	v_add_f32_e32 v162, v162, v10
	s_waitcnt lgkmcnt(0)
	v_add_f32_e32 v163, v163, v11
	ds_bpermute_b32 v8, v4, v160
	ds_bpermute_b32 v9, v4, v161
	ds_bpermute_b32 v10, v4, v162
	ds_bpermute_b32 v11, v4, v163
	s_waitcnt lgkmcnt(3)
	v_add_f32_e32 v160, v160, v8
	s_waitcnt lgkmcnt(2)
	v_add_f32_e32 v161, v161, v9
	s_waitcnt lgkmcnt(1)
	v_add_f32_e32 v162, v162, v10
	s_waitcnt lgkmcnt(0)
	v_add_f32_e32 v163, v163, v11
	ds_bpermute_b32 v8, v5, v160
	ds_bpermute_b32 v9, v5, v161
	ds_bpermute_b32 v10, v5, v162
	ds_bpermute_b32 v11, v5, v163
	s_waitcnt lgkmcnt(3)
	v_add_f32_e32 v160, v160, v8
	s_waitcnt lgkmcnt(2)
	v_add_f32_e32 v161, v161, v9
	s_waitcnt lgkmcnt(1)
	v_add_f32_e32 v162, v162, v10
	s_waitcnt lgkmcnt(0)
	v_add_f32_e32 v163, v163, v11
	ds_bpermute_b32 v8, v6, v160
	ds_bpermute_b32 v9, v6, v161
	ds_bpermute_b32 v10, v6, v162
	ds_bpermute_b32 v11, v6, v163
	s_waitcnt lgkmcnt(3)
	v_add_f32_e32 v160, v160, v8
	s_waitcnt lgkmcnt(2)
	v_add_f32_e32 v161, v161, v9
	s_waitcnt lgkmcnt(1)
	v_add_f32_e32 v162, v162, v10
	s_waitcnt lgkmcnt(0)
	v_add_f32_e32 v163, v163, v11
	ds_bpermute_b32 v8, v7, v160
	ds_bpermute_b32 v9, v7, v161
	ds_bpermute_b32 v10, v7, v162
	ds_bpermute_b32 v11, v7, v163
	s_waitcnt lgkmcnt(3)
	v_add_f32_e32 v160, v160, v8
	s_waitcnt lgkmcnt(2)
	v_add_f32_e32 v161, v161, v9
	s_waitcnt lgkmcnt(1)
	v_add_f32_e32 v162, v162, v10
	s_waitcnt lgkmcnt(0)
	v_add_f32_e32 v163, v163, v11
	s_mov_b32 s7, 0xf800000
	v_fmamk_f32 v160, v160, 0x3a800000, v190
	v_mul_f32_e32 v8, 0x4f800000, v160
	v_cmp_gt_f32_e32 vcc, s7, v160
	s_nop 1
	v_cndmask_b32_e32 v160, v160, v8, vcc
	v_sqrt_f32_e32 v8, v160
	s_nop 0
	v_add_u32_e32 v9, -1, v8
	v_fma_f32 v10, -v9, v8, v160
	v_cmp_ge_f32_e64 s[4:5], 0, v10
	v_add_u32_e32 v10, 1, v8
	s_nop 0
	v_cndmask_b32_e64 v9, v8, v9, s[4:5]
	v_fma_f32 v8, -v10, v8, v160
	v_cmp_lt_f32_e64 s[4:5], 0, v8
	s_nop 1
	v_cndmask_b32_e64 v8, v9, v10, s[4:5]
	v_mul_f32_e32 v9, 0x37800000, v8
	v_cndmask_b32_e32 v8, v8, v9, vcc
	v_cmp_class_f32_e32 vcc, v160, v191
	s_nop 1
	v_cndmask_b32_e32 v160, v8, v160, vcc
	v_div_scale_f32 v8, s[4:5], v160, v160, 1.0
	v_rcp_f32_e32 v9, v8
	s_nop 0
	v_fma_f32 v10, -v8, v9, 1.0
	v_fmac_f32_e32 v9, v10, v9
	v_div_scale_f32 v10, vcc, 1.0, v160, 1.0
	v_mul_f32_e32 v11, v10, v9
	v_fma_f32 v12, -v8, v11, v10
	v_fmac_f32_e32 v11, v12, v9
	v_fma_f32 v8, -v8, v11, v10
	v_div_fmas_f32 v8, v8, v9, v11
	v_div_fixup_f32 v160, v8, v160, 1.0
	s_mov_b32 s7, 0xf800000
	v_fmamk_f32 v161, v161, 0x3a800000, v190
	v_mul_f32_e32 v8, 0x4f800000, v161
	v_cmp_gt_f32_e32 vcc, s7, v161
	s_nop 1
	v_cndmask_b32_e32 v161, v161, v8, vcc
	v_sqrt_f32_e32 v8, v161
	s_nop 0
	v_add_u32_e32 v9, -1, v8
	v_fma_f32 v10, -v9, v8, v161
	v_cmp_ge_f32_e64 s[4:5], 0, v10
	v_add_u32_e32 v10, 1, v8
	s_nop 0
	v_cndmask_b32_e64 v9, v8, v9, s[4:5]
	v_fma_f32 v8, -v10, v8, v161
	v_cmp_lt_f32_e64 s[4:5], 0, v8
	s_nop 1
	v_cndmask_b32_e64 v8, v9, v10, s[4:5]
	v_mul_f32_e32 v9, 0x37800000, v8
	v_cndmask_b32_e32 v8, v8, v9, vcc
	v_cmp_class_f32_e32 vcc, v161, v191
	s_nop 1
	v_cndmask_b32_e32 v161, v8, v161, vcc
	v_div_scale_f32 v8, s[4:5], v161, v161, 1.0
	v_rcp_f32_e32 v9, v8
	s_nop 0
	v_fma_f32 v10, -v8, v9, 1.0
	v_fmac_f32_e32 v9, v10, v9
	v_div_scale_f32 v10, vcc, 1.0, v161, 1.0
	v_mul_f32_e32 v11, v10, v9
	v_fma_f32 v12, -v8, v11, v10
	v_fmac_f32_e32 v11, v12, v9
	v_fma_f32 v8, -v8, v11, v10
	v_div_fmas_f32 v8, v8, v9, v11
	v_div_fixup_f32 v161, v8, v161, 1.0
	s_mov_b32 s7, 0xf800000
	v_fmamk_f32 v162, v162, 0x3a800000, v190
	v_mul_f32_e32 v8, 0x4f800000, v162
	v_cmp_gt_f32_e32 vcc, s7, v162
	s_nop 1
	v_cndmask_b32_e32 v162, v162, v8, vcc
	v_sqrt_f32_e32 v8, v162
	s_nop 0
	v_add_u32_e32 v9, -1, v8
	v_fma_f32 v10, -v9, v8, v162
	v_cmp_ge_f32_e64 s[4:5], 0, v10
	v_add_u32_e32 v10, 1, v8
	s_nop 0
	v_cndmask_b32_e64 v9, v8, v9, s[4:5]
	v_fma_f32 v8, -v10, v8, v162
	v_cmp_lt_f32_e64 s[4:5], 0, v8
	s_nop 1
	v_cndmask_b32_e64 v8, v9, v10, s[4:5]
	v_mul_f32_e32 v9, 0x37800000, v8
	v_cndmask_b32_e32 v8, v8, v9, vcc
	v_cmp_class_f32_e32 vcc, v162, v191
	s_nop 1
	v_cndmask_b32_e32 v162, v8, v162, vcc
	v_div_scale_f32 v8, s[4:5], v162, v162, 1.0
	v_rcp_f32_e32 v9, v8
	s_nop 0
	v_fma_f32 v10, -v8, v9, 1.0
	v_fmac_f32_e32 v9, v10, v9
	v_div_scale_f32 v10, vcc, 1.0, v162, 1.0
	v_mul_f32_e32 v11, v10, v9
	v_fma_f32 v12, -v8, v11, v10
	v_fmac_f32_e32 v11, v12, v9
	v_fma_f32 v8, -v8, v11, v10
	v_div_fmas_f32 v8, v8, v9, v11
	v_div_fixup_f32 v162, v8, v162, 1.0
	s_mov_b32 s7, 0xf800000
	v_fmamk_f32 v163, v163, 0x3a800000, v190
	v_mul_f32_e32 v8, 0x4f800000, v163
	v_cmp_gt_f32_e32 vcc, s7, v163
	s_nop 1
	v_cndmask_b32_e32 v163, v163, v8, vcc
	v_sqrt_f32_e32 v8, v163
	s_nop 0
	v_add_u32_e32 v9, -1, v8
	v_fma_f32 v10, -v9, v8, v163
	v_cmp_ge_f32_e64 s[4:5], 0, v10
	v_add_u32_e32 v10, 1, v8
	s_nop 0
	v_cndmask_b32_e64 v9, v8, v9, s[4:5]
	v_fma_f32 v8, -v10, v8, v163
	v_cmp_lt_f32_e64 s[4:5], 0, v8
	s_nop 1
	v_cndmask_b32_e64 v8, v9, v10, s[4:5]
	v_mul_f32_e32 v9, 0x37800000, v8
	v_cndmask_b32_e32 v8, v8, v9, vcc
	v_cmp_class_f32_e32 vcc, v163, v191
	s_nop 1
	v_cndmask_b32_e32 v163, v8, v163, vcc
	v_div_scale_f32 v8, s[4:5], v163, v163, 1.0
	v_rcp_f32_e32 v9, v8
	s_nop 0
	v_fma_f32 v10, -v8, v9, 1.0
	v_fmac_f32_e32 v9, v10, v9
	v_div_scale_f32 v10, vcc, 1.0, v163, 1.0
	v_mul_f32_e32 v11, v10, v9
	v_fma_f32 v12, -v8, v11, v10
	v_fmac_f32_e32 v11, v12, v9
	v_fma_f32 v8, -v8, v11, v10
	v_div_fmas_f32 v8, v8, v9, v11
	v_div_fixup_f32 v163, v8, v163, 1.0
	s_waitcnt vmcnt(24)
	s_lshl_b32 s7, s8, 11
	s_add_u32 s4, s46, s7
	s_addc_u32 s5, s47, 0
	s_add_u32 s4, s4, 0x8900000
	s_addc_u32 s5, s5, 0
	v_mul_f32_e32 v19, v19, v160
	v_mul_f32_e32 v19, v83, v19
	v_mul_f32_e32 v18, v18, v160
	v_mul_f32_e32 v18, v82, v18
	v_mul_f32_e32 v17, v17, v160
	v_mul_f32_e32 v17, v81, v17
	v_mul_f32_e32 v16, v16, v160
	v_mul_f32_e32 v16, v80, v16
	v_add_f32_e32 v11, 1.0, v99
	v_fma_f32 v19, v11, v19, v115
	v_add_f32_e32 v10, 1.0, v98
	v_fma_f32 v18, v10, v18, v114
	v_add_f32_e32 v9, 1.0, v97
	v_fma_f32 v17, v9, v17, v113
	v_add_f32_e32 v8, 1.0, v96
	v_fma_f32 v16, v8, v16, v112
	v_mul_f32_e32 v23, v23, v160
	v_mul_f32_e32 v23, v87, v23
	v_mul_f32_e32 v22, v22, v160
	v_mul_f32_e32 v22, v86, v22
	v_mul_f32_e32 v21, v21, v160
	v_mul_f32_e32 v21, v85, v21
	v_mul_f32_e32 v20, v20, v160
	v_mul_f32_e32 v20, v84, v20
	v_add_f32_e32 v11, 1.0, v103
	v_fma_f32 v23, v11, v23, v119
	v_add_f32_e32 v10, 1.0, v102
	v_fma_f32 v22, v10, v22, v118
	v_add_f32_e32 v9, 1.0, v101
	v_fma_f32 v21, v9, v21, v117
	v_add_f32_e32 v8, 1.0, v100
	v_fma_f32 v20, v8, v20, v116
	v_cvt_pk_bf16_f32 v16, v16, v17
	v_cvt_pk_bf16_f32 v17, v18, v19
	v_cvt_pk_bf16_f32 v18, v20, v21
	v_cvt_pk_bf16_f32 v19, v22, v23
	global_store_dwordx4 v1, v[16:19], s[4:5]
	v_mul_f32_e32 v27, v27, v160
	v_mul_f32_e32 v27, v91, v27
	v_mul_f32_e32 v26, v26, v160
	v_mul_f32_e32 v26, v90, v26
	v_mul_f32_e32 v25, v25, v160
	v_mul_f32_e32 v25, v89, v25
	v_mul_f32_e32 v24, v24, v160
	v_mul_f32_e32 v24, v88, v24
	v_add_f32_e32 v11, 1.0, v107
	v_fma_f32 v27, v11, v27, v123
	v_add_f32_e32 v10, 1.0, v106
	v_fma_f32 v26, v10, v26, v122
	v_add_f32_e32 v9, 1.0, v105
	v_fma_f32 v25, v9, v25, v121
	v_add_f32_e32 v8, 1.0, v104
	v_fma_f32 v24, v8, v24, v120
	v_mul_f32_e32 v31, v31, v160
	v_mul_f32_e32 v31, v95, v31
	v_mul_f32_e32 v30, v30, v160
	v_mul_f32_e32 v30, v94, v30
	v_mul_f32_e32 v29, v29, v160
	v_mul_f32_e32 v29, v93, v29
	v_mul_f32_e32 v28, v28, v160
	v_mul_f32_e32 v28, v92, v28
	v_add_f32_e32 v11, 1.0, v111
	v_fma_f32 v31, v11, v31, v127
	v_add_f32_e32 v10, 1.0, v110
	v_fma_f32 v30, v10, v30, v126
	v_add_f32_e32 v9, 1.0, v109
	v_fma_f32 v29, v9, v29, v125
	v_add_f32_e32 v8, 1.0, v108
	v_fma_f32 v28, v8, v28, v124
	v_cvt_pk_bf16_f32 v24, v24, v25
	v_cvt_pk_bf16_f32 v25, v26, v27
	v_cvt_pk_bf16_f32 v26, v28, v29
	v_cvt_pk_bf16_f32 v27, v30, v31
	global_store_dwordx4 v1, v[24:27], s[4:5] offset:1024
	s_sub_i32 s7, s10, 0x1000
	s_lshr_b32 s7, s7, 11
	s_add_i32 s7, s7, 1
	s_cmpk_lt_i32 s10, 0x1000
	s_cselect_b32 s7, 0, s7
	s_mulk_i32 s7, 0x6000
	s_add_i32 s7, s7, 0x0
	s_add_u32 s4, s14, s7
	s_addc_u32 s5, s15, 0
	global_load_dwordx4 v[112:115], v0, s[4:5]
	global_load_dwordx4 v[116:119], v0, s[4:5] offset:16
	global_load_dwordx4 v[120:123], v0, s[4:5] offset:2048
	global_load_dwordx4 v[124:127], v0, s[4:5] offset:2064
	s_add_u32 s4, s4, 0x1000
	s_addc_u32 s5, s5, 0
	global_load_dwordx4 v[96:99], v0, s[4:5]
	global_load_dwordx4 v[100:103], v0, s[4:5] offset:16
	global_load_dwordx4 v[104:107], v0, s[4:5] offset:2048
	global_load_dwordx4 v[108:111], v0, s[4:5] offset:2064
	s_waitcnt vmcnt(26)
	s_lshl_b32 s7, s9, 11
	s_add_u32 s4, s46, s7
	s_addc_u32 s5, s47, 0
	s_add_u32 s4, s4, 0x8900000
	s_addc_u32 s5, s5, 0
	v_mul_f32_e32 v35, v35, v161
	v_mul_f32_e32 v35, v83, v35
	v_mul_f32_e32 v34, v34, v161
	v_mul_f32_e32 v34, v82, v34
	v_mul_f32_e32 v33, v33, v161
	v_mul_f32_e32 v33, v81, v33
	v_mul_f32_e32 v32, v32, v161
	v_mul_f32_e32 v32, v80, v32
	v_add_f32_e32 v11, 1.0, v131
	v_fma_f32 v35, v11, v35, v147
	v_add_f32_e32 v10, 1.0, v130
	v_fma_f32 v34, v10, v34, v146
	v_add_f32_e32 v9, 1.0, v129
	v_fma_f32 v33, v9, v33, v145
	v_add_f32_e32 v8, 1.0, v128
	v_fma_f32 v32, v8, v32, v144
	v_mul_f32_e32 v39, v39, v161
	v_mul_f32_e32 v39, v87, v39
	v_mul_f32_e32 v38, v38, v161
	v_mul_f32_e32 v38, v86, v38
	v_mul_f32_e32 v37, v37, v161
	v_mul_f32_e32 v37, v85, v37
	v_mul_f32_e32 v36, v36, v161
	v_mul_f32_e32 v36, v84, v36
	v_add_f32_e32 v11, 1.0, v135
	v_fma_f32 v39, v11, v39, v151
	v_add_f32_e32 v10, 1.0, v134
	v_fma_f32 v38, v10, v38, v150
	v_add_f32_e32 v9, 1.0, v133
	v_fma_f32 v37, v9, v37, v149
	v_add_f32_e32 v8, 1.0, v132
	v_fma_f32 v36, v8, v36, v148
	v_cvt_pk_bf16_f32 v32, v32, v33
	v_cvt_pk_bf16_f32 v33, v34, v35
	v_cvt_pk_bf16_f32 v34, v36, v37
	v_cvt_pk_bf16_f32 v35, v38, v39
	global_store_dwordx4 v1, v[32:35], s[4:5]
	v_mul_f32_e32 v43, v43, v161
	v_mul_f32_e32 v43, v91, v43
	v_mul_f32_e32 v42, v42, v161
	v_mul_f32_e32 v42, v90, v42
	v_mul_f32_e32 v41, v41, v161
	v_mul_f32_e32 v41, v89, v41
	v_mul_f32_e32 v40, v40, v161
	v_mul_f32_e32 v40, v88, v40
	v_add_f32_e32 v11, 1.0, v139
	v_fma_f32 v43, v11, v43, v155
	v_add_f32_e32 v10, 1.0, v138
	v_fma_f32 v42, v10, v42, v154
	v_add_f32_e32 v9, 1.0, v137
	v_fma_f32 v41, v9, v41, v153
	v_add_f32_e32 v8, 1.0, v136
	v_fma_f32 v40, v8, v40, v152
	v_mul_f32_e32 v47, v47, v161
	v_mul_f32_e32 v47, v95, v47
	v_mul_f32_e32 v46, v46, v161
	v_mul_f32_e32 v46, v94, v46
	v_mul_f32_e32 v45, v45, v161
	v_mul_f32_e32 v45, v93, v45
	v_mul_f32_e32 v44, v44, v161
	v_mul_f32_e32 v44, v92, v44
	v_add_f32_e32 v11, 1.0, v143
	v_fma_f32 v47, v11, v47, v159
	v_add_f32_e32 v10, 1.0, v142
	v_fma_f32 v46, v10, v46, v158
	v_add_f32_e32 v9, 1.0, v141
	v_fma_f32 v45, v9, v45, v157
	v_add_f32_e32 v8, 1.0, v140
	v_fma_f32 v44, v8, v44, v156
	v_cvt_pk_bf16_f32 v40, v40, v41
	v_cvt_pk_bf16_f32 v41, v42, v43
	v_cvt_pk_bf16_f32 v42, v44, v45
	v_cvt_pk_bf16_f32 v43, v46, v47
	global_store_dwordx4 v1, v[40:43], s[4:5] offset:1024
	s_sub_i32 s7, s11, 0x1000
	s_lshr_b32 s7, s7, 11
	s_add_i32 s7, s7, 1
	s_cmpk_lt_i32 s11, 0x1000
	s_cselect_b32 s7, 0, s7
	s_mulk_i32 s7, 0x6000
	s_add_i32 s7, s7, 0x0
	s_add_u32 s4, s14, s7
	s_addc_u32 s5, s15, 0
	global_load_dwordx4 v[144:147], v0, s[4:5]
	global_load_dwordx4 v[148:151], v0, s[4:5] offset:16
	global_load_dwordx4 v[152:155], v0, s[4:5] offset:2048
	global_load_dwordx4 v[156:159], v0, s[4:5] offset:2064
	s_add_u32 s4, s4, 0x1000
	s_addc_u32 s5, s5, 0
	global_load_dwordx4 v[128:131], v0, s[4:5]
	global_load_dwordx4 v[132:135], v0, s[4:5] offset:16
	global_load_dwordx4 v[136:139], v0, s[4:5] offset:2048
	global_load_dwordx4 v[140:143], v0, s[4:5] offset:2064
	s_waitcnt vmcnt(10)
	s_lshl_b32 s7, s10, 11
	s_add_u32 s4, s46, s7
	s_addc_u32 s5, s47, 0
	s_add_u32 s4, s4, 0x8900000
	s_addc_u32 s5, s5, 0
	v_mul_f32_e32 v51, v51, v162
	v_mul_f32_e32 v51, v83, v51
	v_mul_f32_e32 v50, v50, v162
	v_mul_f32_e32 v50, v82, v50
	v_mul_f32_e32 v49, v49, v162
	v_mul_f32_e32 v49, v81, v49
	v_mul_f32_e32 v48, v48, v162
	v_mul_f32_e32 v48, v80, v48
	v_add_f32_e32 v11, 1.0, v99
	v_fma_f32 v51, v11, v51, v115
	v_add_f32_e32 v10, 1.0, v98
	v_fma_f32 v50, v10, v50, v114
	v_add_f32_e32 v9, 1.0, v97
	v_fma_f32 v49, v9, v49, v113
	v_add_f32_e32 v8, 1.0, v96
	v_fma_f32 v48, v8, v48, v112
	v_mul_f32_e32 v55, v55, v162
	v_mul_f32_e32 v55, v87, v55
	v_mul_f32_e32 v54, v54, v162
	v_mul_f32_e32 v54, v86, v54
	v_mul_f32_e32 v53, v53, v162
	v_mul_f32_e32 v53, v85, v53
	v_mul_f32_e32 v52, v52, v162
	v_mul_f32_e32 v52, v84, v52
	v_add_f32_e32 v11, 1.0, v103
	v_fma_f32 v55, v11, v55, v119
	v_add_f32_e32 v10, 1.0, v102
	v_fma_f32 v54, v10, v54, v118
	v_add_f32_e32 v9, 1.0, v101
	v_fma_f32 v53, v9, v53, v117
	v_add_f32_e32 v8, 1.0, v100
	v_fma_f32 v52, v8, v52, v116
	v_cvt_pk_bf16_f32 v48, v48, v49
	v_cvt_pk_bf16_f32 v49, v50, v51
	v_cvt_pk_bf16_f32 v50, v52, v53
	v_cvt_pk_bf16_f32 v51, v54, v55
	global_store_dwordx4 v1, v[48:51], s[4:5]
	v_mul_f32_e32 v59, v59, v162
	v_mul_f32_e32 v59, v91, v59
	v_mul_f32_e32 v58, v58, v162
	v_mul_f32_e32 v58, v90, v58
	v_mul_f32_e32 v57, v57, v162
	v_mul_f32_e32 v57, v89, v57
	v_mul_f32_e32 v56, v56, v162
	v_mul_f32_e32 v56, v88, v56
	v_add_f32_e32 v11, 1.0, v107
	v_fma_f32 v59, v11, v59, v123
	v_add_f32_e32 v10, 1.0, v106
	v_fma_f32 v58, v10, v58, v122
	v_add_f32_e32 v9, 1.0, v105
	v_fma_f32 v57, v9, v57, v121
	v_add_f32_e32 v8, 1.0, v104
	v_fma_f32 v56, v8, v56, v120
	v_mul_f32_e32 v63, v63, v162
	v_mul_f32_e32 v63, v95, v63
	v_mul_f32_e32 v62, v62, v162
	v_mul_f32_e32 v62, v94, v62
	v_mul_f32_e32 v61, v61, v162
	v_mul_f32_e32 v61, v93, v61
	v_mul_f32_e32 v60, v60, v162
	v_mul_f32_e32 v60, v92, v60
	v_add_f32_e32 v11, 1.0, v111
	v_fma_f32 v63, v11, v63, v127
	v_add_f32_e32 v10, 1.0, v110
	v_fma_f32 v62, v10, v62, v126
	v_add_f32_e32 v9, 1.0, v109
	v_fma_f32 v61, v9, v61, v125
	v_add_f32_e32 v8, 1.0, v108
	v_fma_f32 v60, v8, v60, v124
	v_cvt_pk_bf16_f32 v56, v56, v57
	v_cvt_pk_bf16_f32 v57, v58, v59
	v_cvt_pk_bf16_f32 v58, v60, v61
	v_cvt_pk_bf16_f32 v59, v62, v63
	global_store_dwordx4 v1, v[56:59], s[4:5] offset:1024
	s_waitcnt vmcnt(2)
	s_lshl_b32 s7, s11, 11
	s_add_u32 s4, s46, s7
	s_addc_u32 s5, s47, 0
	s_add_u32 s4, s4, 0x8900000
	s_addc_u32 s5, s5, 0
	v_mul_f32_e32 v67, v67, v163
	v_mul_f32_e32 v67, v83, v67
	v_mul_f32_e32 v66, v66, v163
	v_mul_f32_e32 v66, v82, v66
	v_mul_f32_e32 v65, v65, v163
	v_mul_f32_e32 v65, v81, v65
	v_mul_f32_e32 v64, v64, v163
	v_mul_f32_e32 v64, v80, v64
	v_add_f32_e32 v11, 1.0, v131
	v_fma_f32 v67, v11, v67, v147
	v_add_f32_e32 v10, 1.0, v130
	v_fma_f32 v66, v10, v66, v146
	v_add_f32_e32 v9, 1.0, v129
	v_fma_f32 v65, v9, v65, v145
	v_add_f32_e32 v8, 1.0, v128
	v_fma_f32 v64, v8, v64, v144
	v_mul_f32_e32 v71, v71, v163
	v_mul_f32_e32 v71, v87, v71
	v_mul_f32_e32 v70, v70, v163
	v_mul_f32_e32 v70, v86, v70
	v_mul_f32_e32 v69, v69, v163
	v_mul_f32_e32 v69, v85, v69
	v_mul_f32_e32 v68, v68, v163
	v_mul_f32_e32 v68, v84, v68
	v_add_f32_e32 v11, 1.0, v135
	v_fma_f32 v71, v11, v71, v151
	v_add_f32_e32 v10, 1.0, v134
	v_fma_f32 v70, v10, v70, v150
	v_add_f32_e32 v9, 1.0, v133
	v_fma_f32 v69, v9, v69, v149
	v_add_f32_e32 v8, 1.0, v132
	v_fma_f32 v68, v8, v68, v148
	v_cvt_pk_bf16_f32 v64, v64, v65
	v_cvt_pk_bf16_f32 v65, v66, v67
	v_cvt_pk_bf16_f32 v66, v68, v69
	v_cvt_pk_bf16_f32 v67, v70, v71
	global_store_dwordx4 v1, v[64:67], s[4:5]
	v_mul_f32_e32 v75, v75, v163
	v_mul_f32_e32 v75, v91, v75
	v_mul_f32_e32 v74, v74, v163
	v_mul_f32_e32 v74, v90, v74
	v_mul_f32_e32 v73, v73, v163
	v_mul_f32_e32 v73, v89, v73
	v_mul_f32_e32 v72, v72, v163
	v_mul_f32_e32 v72, v88, v72
	v_add_f32_e32 v11, 1.0, v139
	v_fma_f32 v75, v11, v75, v155
	v_add_f32_e32 v10, 1.0, v138
	v_fma_f32 v74, v10, v74, v154
	v_add_f32_e32 v9, 1.0, v137
	v_fma_f32 v73, v9, v73, v153
	v_add_f32_e32 v8, 1.0, v136
	v_fma_f32 v72, v8, v72, v152
	v_mul_f32_e32 v79, v79, v163
	v_mul_f32_e32 v79, v95, v79
	v_mul_f32_e32 v78, v78, v163
	v_mul_f32_e32 v78, v94, v78
	v_mul_f32_e32 v77, v77, v163
	v_mul_f32_e32 v77, v93, v77
	v_mul_f32_e32 v76, v76, v163
	v_mul_f32_e32 v76, v92, v76
	v_add_f32_e32 v11, 1.0, v143
	v_fma_f32 v79, v11, v79, v159
	v_add_f32_e32 v10, 1.0, v142
	v_fma_f32 v78, v10, v78, v158
	v_add_f32_e32 v9, 1.0, v141
	v_fma_f32 v77, v9, v77, v157
	v_add_f32_e32 v8, 1.0, v140
	v_fma_f32 v76, v8, v76, v156
	v_cvt_pk_bf16_f32 v72, v72, v73
	v_cvt_pk_bf16_f32 v73, v74, v75
	v_cvt_pk_bf16_f32 v74, v76, v77
	v_cvt_pk_bf16_f32 v75, v78, v79
	global_store_dwordx4 v1, v[72:75], s[4:5] offset:1024
	s_lshl_b32 s7, s6, 2
	s_add_i32 s3, s3, s7
	s_cmpk_lt_i32 s3, 0x2000
	s_cbranch_scc1 .Lnorm1f_loop

.Lxb_have:
	v_readfirstlane_b32 s10, v0
	v_readfirstlane_b32 s11, v1
	v_readlane_b32 s8, v240, 60
	s_add_u32 s12, s6, s3
	s_addc_u32 s13, s7, 0
	v_mov_b32_e32 v2, 1
	s_add_i32 s101, s101, 1
	s_mul_i32 s10, s10, s101
	v_mov_b32_e32 v4, s8
	ds_read_b32 v4, v4 offset:8
	global_atomic_add v3, v196, v2, s[12:13] offset:1024 sc0
	buffer_inv sc1
	v_readlane_b32 s8, v240, 0
	s_lshl_b32 s8, s8, 6
	s_add_u32 s8, s8, 0x4000
	s_add_u32 s14, s6, s8
	s_addc_u32 s15, s7, 0
	s_mov_b32 s9, 0
	s_waitcnt lgkmcnt(0)
	v_readfirstlane_b32 s8, v4
	s_cmp_eq_u32 s8, 1
	s_cbranch_scc0 .Lxb_grid
	s_mov_b32 s8, 0x3cfdf3f4
	s_bitcmp1_b32 s8, s70
	s_cbranch_scc0 .Lxb_grid
	s_waitcnt vmcnt(1)
	v_add_u32_e32 v3, 1, v3
	v_cmp_gt_u32_e32 vcc, s10, v3
	s_cbranch_vccz .Lxb_done
